# v60 + last layer's second FFN (out-proj -> norm -> SwiGLU -> FFN-down) as a chain of XCD-local barriers with XCD-aligned norm rows; final grid sync dropped
# speedup vs baseline: 1.0144x; 1.0005x over previous
; DI const float* in_ptr(const Args& AR, int i) { asm volatile("" : "+s"(i)); return GLOBAL_PTR(const float, AR.in[i]); }
; DI void norm_phase(Frame& F, const float* srcL, const float* srcC, const float* g, const float* modl, int sub) {
;     const int gw = F.vcu * 8 + F.wave; constexpr int RPW = TT / 2048;
;     bf16_t* H = WSP(bf16_t, WS_H);
;     int cur_bi = -1; f32x4 gs[4], sh[4];
;     for (int row = gw * RPW; row < gw * RPW + RPW; ++row) {
;         const int bi = row < TL ? (row >> 12) : 16;
;         if (bi != cur_bi) { cur_bi = bi; const float* mp = modl + (size_t)bi * MODW + sub * 3072;
; #pragma unroll
;             for (int j = 0; j < 4; ++j) { const int k = (F.lane + 64 * j) * 4; const f32x4 gg = *(const f32x4*)(g + k), sc = *(const f32x4*)(mp + 1024 + k); sh[j] = *(const f32x4*)(mp + k); gs[j] = gg * (sc + 1.0f); } }
; __global__ void __launch_bounds__(512, 2) fwd_megakernel(Args args) {
;     ...
;             if (type == T_NORM) {
;                 const int sub = op == 0 ? 0 : (op == 3 ? 1 : 2);
;                 if (even && op == 3) norm_pair_phase(F, srcL, srcC, in_ptr(AR, 4) + (size_t)(l * 3 + sub) * DM, modl, sub);
;                 else norm_phase(F, srcL, srcC, in_ptr(AR, 4) + (size_t)(l * 3 + sub) * DM, modl, sub);
.LBB0_522:
	s_andn2_b64 vcc, exec, s[4:5]
	s_cbranch_vccnz .LBB0_578
	s_cmp_lg_u32 s35, 1
	s_cbranch_scc1 .LBB0_578
	s_cmp_eq_u32 s44, 3
	v_readlane_b32 s6, v255, 17
	s_cselect_b64 s[4:5], -1, 0
	v_readlane_b32 s7, v255, 18
	s_and_b64 s[6:7], s[6:7], s[4:5]
	s_andn2_b64 vcc, exec, s[6:7]
	s_mov_b64 s[6:7], -1
	v_readlane_b32 s12, v255, 28
	s_cbranch_vccz .LBB0_532
	s_and_b64 s[4:5], s[4:5], exec
	s_cselect_b32 s2, 1, 2
	s_cmp_lg_u32 s44, 0
	s_mov_b32 s4, 4
	s_cselect_b32 s2, s2, 0
	s_ashr_i32 s5, s4, 31
	s_lshl_b64 s[4:5], s[4:5], 3
	s_add_u32 s4, s0, s4
	s_mul_i32 s6, s36, 3
	s_addc_u32 s5, s1, s5
	s_add_i32 s6, s2, s6
	v_cmp_lt_i32_e32 vcc, v181, v180
	s_lshl_b32 s20, s6, 10
	s_load_dwordx2 s[4:5], s[4:5], 0x0
	v_cndmask_b32_e32 v0, v169, v181, vcc
	v_cmp_lt_i32_e32 vcc, v182, v180
	s_lshl_b64 s[6:7], s[20:21], 2
	v_lshlrev_b32_e32 v35, 2, v0
	v_cndmask_b32_e32 v0, v169, v182, vcc
	v_cmp_lt_i32_e32 vcc, v183, v180
	s_waitcnt lgkmcnt(0)
	s_add_u32 s6, s4, s6
	v_lshlrev_b32_e32 v40, 2, v0
	v_cndmask_b32_e32 v0, v169, v183, vcc
	v_cmp_lt_i32_e32 vcc, v192, v180
	s_addc_u32 s7, s5, s7
	s_lshl_b32 s4, s12, 3
	v_lshlrev_b32_e32 v41, 2, v0
	v_cndmask_b32_e32 v0, v169, v192, vcc
	v_cmp_lt_i32_e32 vcc, v254, v180
	s_add_i32 s4, s4, s50
	v_lshlrev_b32_e32 v42, 2, v0
	v_cndmask_b32_e32 v0, v169, v254, vcc
	v_cmp_lt_i32_e32 vcc, v186, v180
	s_mulk_i32 s2, 0x3000
	s_mul_i32 s4, s4, 34
	v_lshlrev_b32_e32 v43, 2, v0
	v_cndmask_b32_e32 v0, v169, v186, vcc
	s_add_u32 s2, s29, s2
	v_lshlrev_b32_e32 v44, 2, v0
	s_addc_u32 s10, s94, 0
	v_lshlrev_b32_e32 v0, 4, v194
	s_ashr_i32 s5, s4, 31
	s_add_i32 s11, s4, 33
	v_lshlrev_b32_e32 v34, 2, v194
	v_lshl_add_u64 v[36:37], s[6:7], 0, v[0:1]
	s_lshl_b64 s[6:7], s[4:5], 12
	v_or_b32_e32 v16, 0x100, v34
	v_lshlrev_b32_e32 v0, 3, v194
	s_add_u32 s6, s54, s6
	s_mul_i32 s8, s12, 0x110
	s_mul_i32 s9, s50, 34
	v_mov_b32_e32 v2, v1
	v_mov_b32_e32 v3, v1
	v_mov_b32_e32 v4, v1
	v_mov_b32_e32 v5, v1
	v_mov_b32_e32 v6, v1
	v_mov_b32_e32 v7, v1
	v_mov_b32_e32 v8, v1
	v_mov_b32_e32 v9, v1
	v_mov_b32_e32 v10, v1
	v_mov_b32_e32 v11, v1
	v_mov_b32_e32 v12, v1
	v_mov_b32_e32 v13, v1
	v_mov_b32_e32 v14, v1
	v_mov_b32_e32 v15, v1
	v_or_b32_e32 v18, 0x200, v34
	v_or_b32_e32 v20, 0x300, v34
	v_lshl_add_u64 v[38:39], s[58:59], 0, v[0:1]
	s_addc_u32 s7, s55, s7
	s_add_i32 s8, s8, s9
	v_mov_b32_e32 v0, v1
	v_lshlrev_b32_e32 v45, 2, v16
	v_mov_b64_e32 v[16:17], v[14:15]
	s_mov_b32 s17, -1
	s_add_i32 s16, s8, -1
	v_lshlrev_b32_e32 v46, 2, v18
	v_lshlrev_b32_e32 v47, 2, v20
	v_mov_b64_e32 v[14:15], v[12:13]
	v_mov_b64_e32 v[12:13], v[10:11]
	v_mov_b64_e32 v[10:11], v[8:9]
	v_mov_b64_e32 v[8:9], v[6:7]
	v_mov_b64_e32 v[6:7], v[4:5]
	v_mov_b64_e32 v[4:5], v[2:3]
	v_mov_b64_e32 v[2:3], v[0:1]
	s_mov_b32 s101, 0
	s_cmp_eq_u32 s98, 6
	s_cbranch_scc0 .Lnp_not6
	s_lshl_b32 s8, s12, 3
	s_add_u32 s8, s8, s50
	s_lshl_b32 s4, s8, 5
	s_add_u32 s11, s4, 31
	s_mov_b32 s5, 0
	s_sub_u32 s16, s4, 1
	s_lshl_b64 s[6:7], s[4:5], 12
	s_add_u32 s6, s54, s6
	s_addc_u32 s7, s55, s7
	s_branch .Lnp_nosplit
.Lnp_not6:
	s_cmp_eq_u32 s98, 2
	s_cbranch_scc0 .Lnp_nosplit
	s_and_b32 s99, s12, 31
	s_lshr_b32 s8, s12, 5
	s_cmp_lt_u32 s99, 8
	s_cbranch_scc0 .Lnp_classB
	s_mov_b64 s[18:19], exec
	v_readlane_b32 s30, v255, 3
	v_readlane_b32 s31, v255, 4
	s_and_b64 s[30:31], s[18:19], s[30:31]
	s_mov_b64 exec, s[30:31]
	s_cbranch_execz .Lnp_wdone_a
	s_lshl_b32 s9, s100, 6

; #define GRID_SYNC() do { nbar += (unsigned)gridDim.x; grid_barrier(barw, nbar); } while (0)
; DI void grid_barrier(unsigned* cnt, unsigned target) {
;     asm volatile("s_waitcnt vmcnt(0) lgkmcnt(0)" ::: "memory");
;     __syncthreads();
;     if (threadIdx.x == 0) {
;         __builtin_amdgcn_fence(__ATOMIC_RELEASE, "agent");
;         asm volatile("s_waitcnt vmcnt(0)" ::: "memory");
;         __hip_atomic_fetch_add(cnt, 1u, __ATOMIC_RELAXED, __HIP_MEMORY_SCOPE_AGENT);
;         while (__hip_atomic_load(cnt, __ATOMIC_RELAXED, __HIP_MEMORY_SCOPE_AGENT) < target) __builtin_amdgcn_s_sleep(2);
;         __builtin_amdgcn_fence(__ATOMIC_ACQUIRE, "agent");
;         asm volatile("s_waitcnt vmcnt(0)" ::: "memory");
;     }
;     __syncthreads();
; }
; __global__ void __launch_bounds__(512, 2) fwd_megakernel(Args args) {
;     ...
;             if (!(op == 4 || op == 6 || op == 7 || skip0)) GRID_SYNC();
.Lcs_b_normal:
	s_cmp_ge_u32 s98, 6
	s_cbranch_scc0 .Ll3_not
	s_cmp_eq_u32 s98, 8
	s_cbranch_scc0 .Ll3_mid
	s_mov_b32 s98, 0
	s_branch .LBB0_585
.Ll3_mid:
	s_waitcnt vmcnt(0) lgkmcnt(0)
	s_barrier
	v_readlane_b32 s10, v255, 60
	s_add_u32 s10, s10, 1
	s_nop 0
	v_writelane_b32 v255, s10, 60
	s_lshl_b32 s10, s10, 5
	v_readlane_b32 s2, v255, 0
	s_mov_b64 s[4:5], exec
	v_readlane_b32 s6, v255, 3
	v_readlane_b32 s7, v255, 4
	s_and_b64 s[6:7], s[4:5], s[6:7]
	s_mov_b64 exec, s[6:7]
	s_cbranch_execz .Llb_L3m
	s_and_b32 s3, s2, 7
	s_lshl_b32 s3, s3, 2
	s_add_u32 s8, s14, s3
	s_addc_u32 s9, s15, 0
	v_mov_b32_e32 v0, 1
	global_atomic_add v1, v0, s[8:9] offset:128
.Llp_L3m:
	global_load_dword v0, v1, s[8:9] offset:128 sc1
	s_waitcnt vmcnt(0)
	v_cmp_gt_u32_e32 vcc, s10, v0
	s_cbranch_vccz .Lli_L3m
	s_sleep 1
	s_branch .Llp_L3m

; #define GRID_SYNC() do { nbar += (unsigned)gridDim.x; grid_barrier(barw, nbar); } while (0)
; DI void grid_barrier(unsigned* cnt, unsigned target) {
;     asm volatile("s_waitcnt vmcnt(0) lgkmcnt(0)" ::: "memory");
;     __syncthreads();
;     if (threadIdx.x == 0) {
;         __builtin_amdgcn_fence(__ATOMIC_RELEASE, "agent");
;         asm volatile("s_waitcnt vmcnt(0)" ::: "memory");
;         __hip_atomic_fetch_add(cnt, 1u, __ATOMIC_RELAXED, __HIP_MEMORY_SCOPE_AGENT);
;         while (__hip_atomic_load(cnt, __ATOMIC_RELAXED, __HIP_MEMORY_SCOPE_AGENT) < target) __builtin_amdgcn_s_sleep(2);
;         __builtin_amdgcn_fence(__ATOMIC_ACQUIRE, "agent");
;         asm volatile("s_waitcnt vmcnt(0)" ::: "memory");
;     }
;     __syncthreads();
; }
; __global__ void __launch_bounds__(512, 2) fwd_megakernel(Args args) {
;     ...
;             if (!(op == 4 || op == 6 || op == 7 || skip0)) GRID_SYNC();
.Llb_L3m:
	s_mov_b64 exec, s[4:5]
	s_barrier
	s_add_u32 s98, s98, 1
	s_branch .LBB0_585

; #define GRID_SYNC() do { nbar += (unsigned)gridDim.x; grid_barrier(barw, nbar); } while (0)
; DI void grid_barrier(unsigned* cnt, unsigned target) {
;     asm volatile("s_waitcnt vmcnt(0) lgkmcnt(0)" ::: "memory");
;     __syncthreads();
;     if (threadIdx.x == 0) {
;         __builtin_amdgcn_fence(__ATOMIC_RELEASE, "agent");
;         asm volatile("s_waitcnt vmcnt(0)" ::: "memory");
;         __hip_atomic_fetch_add(cnt, 1u, __ATOMIC_RELAXED, __HIP_MEMORY_SCOPE_AGENT);
;         while (__hip_atomic_load(cnt, __ATOMIC_RELAXED, __HIP_MEMORY_SCOPE_AGENT) < target) __builtin_amdgcn_s_sleep(2);
;         __builtin_amdgcn_fence(__ATOMIC_ACQUIRE, "agent");
;         asm volatile("s_waitcnt vmcnt(0)" ::: "memory");
;     }
;     __syncthreads();
; }
; __global__ void __launch_bounds__(512, 2) fwd_megakernel(Args args) {
;     ...
;             if (!(op == 4 || op == 6 || op == 7 || skip0)) GRID_SYNC();
.Lxl_not2:
	s_cmp_eq_u32 s36, 3
	s_cbranch_scc0 .Lxl_l012
	s_cmp_eq_u32 s44, 10
	s_cbranch_scc0 .Lxl_no
	s_waitcnt vmcnt(0) lgkmcnt(0)
	s_barrier
	v_readlane_b32 s10, v255, 60
	s_add_u32 s10, s10, 1
	s_nop 0
	v_writelane_b32 v255, s10, 60
	s_lshl_b32 s10, s10, 5
	v_readlane_b32 s2, v255, 0
	s_mov_b64 s[4:5], exec
	v_readlane_b32 s6, v255, 3
	v_readlane_b32 s7, v255, 4
	s_and_b64 s[6:7], s[4:5], s[6:7]
	s_mov_b64 exec, s[6:7]
	s_cbranch_execz .Llb_L3s
	s_and_b32 s3, s2, 7
	s_lshl_b32 s3, s3, 2
	s_add_u32 s8, s14, s3
	s_addc_u32 s9, s15, 0
	v_mov_b32_e32 v0, 1
	global_atomic_add v1, v0, s[8:9] offset:128

; #define GRID_SYNC() do { nbar += (unsigned)gridDim.x; grid_barrier(barw, nbar); } while (0)
; DI void grid_barrier(unsigned* cnt, unsigned target) {
;     asm volatile("s_waitcnt vmcnt(0) lgkmcnt(0)" ::: "memory");
;     __syncthreads();
;     if (threadIdx.x == 0) {
;         __builtin_amdgcn_fence(__ATOMIC_RELEASE, "agent");
;         asm volatile("s_waitcnt vmcnt(0)" ::: "memory");
;         __hip_atomic_fetch_add(cnt, 1u, __ATOMIC_RELAXED, __HIP_MEMORY_SCOPE_AGENT);
;         while (__hip_atomic_load(cnt, __ATOMIC_RELAXED, __HIP_MEMORY_SCOPE_AGENT) < target) __builtin_amdgcn_s_sleep(2);
;         __builtin_amdgcn_fence(__ATOMIC_ACQUIRE, "agent");
;         asm volatile("s_waitcnt vmcnt(0)" ::: "memory");
;     }
;     __syncthreads();
; }
; __global__ void __launch_bounds__(512, 2) fwd_megakernel(Args args) {
;     ...
;             if (!(op == 4 || op == 6 || op == 7 || skip0)) GRID_SYNC();
.Llb_L3s:
	s_mov_b64 exec, s[4:5]
	s_barrier
	s_mov_b32 s98, 6
	s_branch .LBB0_585
.Lxl_l012:
	s_cmp_eq_u32 s44, 10
	s_cbranch_scc1 .Lxl_yes
	s_cmp_eq_u32 s44, 13
	s_cbranch_scc0 .Lxl_no
